# HGRN2 prompt unit: static priority raise for the state waves (0-3) during the chunk loop
# speedup vs baseline: 1.0002x; 1.0002x over previous
.LBB0_759:
	s_setprio 0
	v_readlane_b32 s56, v255, 9
	s_mov_b64 s[0:1], -1
	s_add_i32 s6, s56, s88
	v_writelane_b32 v255, s6, 9
	s_cmpk_gt_i32 s56, 0xff
	s_cbranch_scc1 .LBB0_758
	s_ashr_i32 s48, s56, 5
	s_ashr_i32 s49, s48, 31
	s_bfe_u32 s63, s56, 0x30002
	v_mov_b32_e32 v101, v0
	s_lshl_b64 s[52:53], s[48:49], 11
	v_mov_b32_e32 v5, s53
	s_lshl_b32 s34, s63, 7
	v_cmp_lt_i32_e32 vcc, s27, v101
	s_and_saveexec_b64 s[0:1], vcc
	s_xor_b64 s[6:7], exec, s[0:1]
	s_cbranch_execz .LBB0_770
	v_cmp_lt_u32_e64 s[0:1], s50, v101
	s_and_saveexec_b64 s[8:9], s[0:1]
	s_xor_b64 s[8:9], exec, s[8:9]
	s_cbranch_execz .LBB0_767
	s_lshl_b64 s[0:1], s[48:49], 18
	s_add_u32 s0, s14, s0
	s_addc_u32 s1, s15, s1
	s_lshl_b32 s35, s34, 2
	s_add_u32 s0, s0, s35
	v_lshlrev_b32_e32 v22, 2, v101
	s_addc_u32 s1, s1, 0
	v_add_u32_e32 v2, 0xfffffd80, v22
	v_lshl_add_u64 v[6:7], v[2:3], 2, s[0:1]
	v_cmp_gt_u32_e64 s[0:1], s51, v101
	s_nop 1
	v_cndmask_b32_e64 v2, 0, v98, s[0:1]
	v_cndmask_b32_e64 v85, 0, v7, s[0:1]
	v_cndmask_b32_e64 v84, 0, v6, s[0:1]
	v_mov_b64_e32 v[14:15], v[2:3]

.LBB0_790:
	s_or_b64 exec, exec, s[0:1]
	s_add_u32 s6, s10, s42
	s_addc_u32 s7, s11, 0
	s_lshl_b32 s66, s63, 2
	s_lshl_b32 s0, s63, 4
	s_add_u32 s0, s36, s0
	s_addc_u32 s1, s37, 0
	s_lshl_b32 s8, s64, 2
	s_add_u32 s0, s0, s8
	s_addc_u32 s1, s1, 0
	s_lshl_b32 s65, s64, 5
	s_lshl_b32 s8, s64, 6
	s_add_u32 s6, s6, s8
	v_mad_u64_u32 v[88:89], s[8:9], v14, 3, 0
	v_mov_b32_e32 v2, v89
	v_mad_u64_u32 v[4:5], s[8:9], v15, 3, v[2:3]
	s_addc_u32 s7, s7, 0
	s_lshl_b64 s[8:9], s[48:49], 22
	v_lshl_or_b32 v2, v99, 11, s8
	s_lshl_b32 s8, s56, 6
	s_and_b32 s8, s8, 0x700
	v_mov_b32_e32 v89, v4
	v_or_b32_e32 v4, s8, v2
	v_mov_b32_e32 v5, s9
	v_lshl_add_u64 v[4:5], v[16:17], 1, v[4:5]
	v_lshl_add_u64 v[90:91], s[86:87], 0, v[4:5]
	v_lshlrev_b64 v[92:93], 2, v[14:15]
	v_mov_b32_e32 v4, v3
	v_mov_b32_e32 v5, v3
	v_mov_b32_e32 v6, v3
	v_mov_b32_e32 v7, v3
	v_mov_b32_e32 v8, v3
	v_mov_b32_e32 v9, v3
	v_mov_b32_e32 v10, v3
	v_mov_b32_e32 v11, v3
	v_mov_b32_e32 v12, v3
	v_mov_b32_e32 v13, v3
	v_mov_b32_e32 v14, v3
	v_mov_b32_e32 v15, v3
	v_mov_b32_e32 v16, v3
	v_mov_b32_e32 v17, v3
	v_mov_b32_e32 v2, v3
	v_mov_b32_e32 v60, 0
	v_mov_b64_e32 v[18:19], v[16:17]
	v_bfe_u32 v100, v101, 5, 1
	v_mov_b32_e32 v105, 0
	s_movk_i32 s49, 0xffe0
	s_mov_b64 s[8:9], 0
	s_mov_b32 s67, -2
	v_mov_b64_e32 v[16:17], v[14:15]
	v_mov_b64_e32 v[14:15], v[12:13]
	v_mov_b64_e32 v[12:13], v[10:11]
	v_mov_b64_e32 v[10:11], v[8:9]
	v_mov_b64_e32 v[8:9], v[6:7]
	v_mov_b64_e32 v[6:7], v[4:5]
	v_mov_b64_e32 v[4:5], v[2:3]
	v_mov_b32_e32 v61, v60
	v_mov_b32_e32 v62, v60
	v_mov_b32_e32 v63, v60
	s_cmp_lt_u32 s33, 4
	s_cbranch_scc0 .Lprio_hg
	s_setprio 1
.Lprio_hg:
	s_waitcnt lgkmcnt(0)
	s_barrier
.LBB0_791:
	v_mov_b32_e32 v96, v99
	v_mov_b32_e32 v94, v101
	v_mov_b32_e32 v95, v100
	s_mov_b64 s[34:35], -1
	s_and_b64 vcc, exec, s[40:41]
	s_cbranch_vccz .LBB0_805
	s_cmp_lt_i32 s33, 7
	s_cbranch_scc1 .LBB0_794
	s_cmp_eq_u32 s33, 7
	s_cselect_b64 s[34:35], -1, 0
	s_cbranch_execz .LBB0_795
	s_branch .LBB0_796
